# v18 + gate/up MoE units: the next unit's row-list loads are no longer waited for at the unit head; consumed behind the first K trip's second counted wait
# speedup vs baseline: 1.0001x; 1.0001x over previous
;     __device__ __forceinline__ bool next(int i, Unit& u) const { u.e = 0; u.aux = 0; u.cnt = 256; return o.next(i, u.pm, u.pn); }
;     __device__ __forceinline__ unsigned arow(const Unit& u, int r) const { return (unsigned)(u.pm * 256 + r); }
; #define G_VOA(dst, u) do { _Pragma("unroll") for (int h = 0; h < 2; ++h) _Pragma("unroll") for (int i = 0; i < 2; ++i) dst[h][i] = (S.arow(u, h * HALF + R0 + 64 * i) * (unsigned)K + (unsigned)C0) * 2u; } while (0)
;     __device__ __forceinline__ unsigned arow(const Unit& u, int r) const {
;         if (!gatherA) return (unsigned)(u.pm * 256 + r);
;         if (!moe) return (unsigned)(u.aux + r);
;         return (r < u.cnt) ? ((unsigned)list[(size_t)u.e * M + u.aux + r] >> 1) : 0u;
;     }
;     ...
;         const bool has_next = S.next(ui + 1, nxt);
;         const char* nB = cB;
;         { unsigned nvo[2][2];
;           if (has_next) { G_VOA(nvo, nxt); nB = (const char*)S.bbase(nxt) + (size_t)nxt.pn * tstep; }
;           else {
; #pragma unroll
;             for (int h = 0; h < 2; ++h)
; #pragma unroll
;                 for (int i = 0; i < 2; ++i) nvo[h][i] = vo[h][i];
;           }
;           *nvo_l = (u32x4){nvo[0][0], nvo[0][1], nvo[1][0], nvo[1][1]}; }
.LBB0_977:
	s_mov_b32 s100, 0
	v_cndmask_b32_e64 v2, 0, 1, s[42:43]
	v_cmp_ne_u32_e64 s[40:41], 1, v2
	s_andn2_b64 vcc, exec, s[42:43]
	v_mov_b64_e32 v[176:177], v[6:7]
	v_mov_b32_e32 v2, v34
	v_mov_b32_e32 v3, v35
	v_mov_b32_e32 v4, v36
	v_mov_b32_e32 v5, v37
	s_cbranch_vccnz .Lmy_gu_zero_last
	s_ashr_i32 s55, s54, 31
	s_ashr_i32 s59, s58, 31
	s_lshl_b64 s[12:13], s[54:55], 18
	s_add_u32 s7, s61, s12
	s_addc_u32 s24, s62, s13
	s_lshl_b64 s[12:13], s[58:59], 2
	s_add_u32 s12, s7, s12
	s_addc_u32 s13, s24, s13
	s_mov_b64 s[24:25], -1
	s_and_b64 vcc, exec, s[46:47]
	s_cbranch_vccz .LBB0_994
	v_lshl_add_u64 v[8:9], v[168:169], 2, s[12:13]
	v_cmp_gt_i32_e32 vcc, s49, v168
	v_mov_b32_e32 v38, 0
	s_and_saveexec_b64 s[24:25], vcc
	global_load_dword v38, v[8:9], off
	s_or_b64 exec, exec, s[24:25]
	v_cmp_gt_i32_e32 vcc, s49, v194
	v_mov_b32_e32 v39, 0
	s_and_saveexec_b64 s[24:25], vcc
	global_load_dword v39, v[8:9], off offset:256
	s_or_b64 exec, exec, s[24:25]
	v_cmp_gt_i32_e32 vcc, s49, v195
	v_mov_b32_e32 v40, 0
	s_and_saveexec_b64 s[24:25], vcc
	global_load_dword v40, v[8:9], off offset:512
	s_or_b64 exec, exec, s[24:25]
	v_cmp_gt_i32_e32 vcc, s49, v204
	v_mov_b32_e32 v41, 0
	s_and_saveexec_b64 s[24:25], vcc
	global_load_dword v41, v[8:9], off offset:768
	s_or_b64 exec, exec, s[24:25]
	s_mov_b32 s100, 1
	s_branch .LBB0_1002

; #define G_STAGE_B(bufoff, gbase) do { G_GLDS((const char*)(gbase) + voffB0, (bufoff) + ldsw); G_GLDS((const char*)(gbase) + vstep64 + voffB0, (bufoff) + ldsw + 8192); } while (0)
; #define G_STAGE_A(bufoff, kofs, v0, v1) do { G_GLDS((const char*)A + (kofs) + (v0), (bufoff) + ldsw); G_GLDS((const char*)A + (kofs) + (v1), (bufoff) + ldsw + 8192); } while (0)
; #define X_LDA(b, h) do { if constexpr (MODE == 2) G_LDA8(A8, b, h); else G_LDA(At, b, h); } while (0)
; #define X_LDB0(b, h) do { if constexpr (MODE == 2) G_LDB8(B08, b, h); else G_LDB(B0, b, h); } while (0)
; #define X_LDB1(b, h) do { if constexpr (MODE == 2) G_LDB8(B18, b, h); else G_LDB(B1, b, h); } while (0)
; #define X_MMA0(ai, bj) do { if constexpr (MODE == 2) G_MMA8(ai, bj, A8, B08); else G_MMA(ai, bj, At, B0); } while (0)
; #define X_MMA1(ai, bj) do { if constexpr (MODE == 2) G_MMA8(ai, bj, A8, B18); else G_MMA(ai, bj, At, B1); } while (0)
; #define G_WAIT_V(n) asm volatile("s_waitcnt vmcnt(" #n ")" ::: "memory")
; #define G_WAIT_L(n) asm volatile("s_waitcnt lgkmcnt(" #n ")" ::: "memory")
; #define G_BAR __builtin_amdgcn_s_barrier()
; #define G_SCHED __builtin_amdgcn_sched_barrier(0)
; #define G_VOA(dst, u) do { _Pragma("unroll") for (int h = 0; h < 2; ++h) _Pragma("unroll") for (int i = 0; i < 2; ++i) dst[h][i] = (S.arow(u, h * HALF + R0 + 64 * i) * (unsigned)K + (unsigned)C0) * 2u; } while (0)
;     ...
;           if (has_next) { G_VOA(nvo, nxt); nB = (const char*)S.bbase(nxt) + (size_t)nxt.pn * tstep; }
;           else {
; #pragma unroll
;             for (int h = 0; h < 2; ++h)
; #pragma unroll
;                 for (int i = 0; i < 2; ++i) nvo[h][i] = vo[h][i];
;           }
;           *nvo_l = (u32x4){nvo[0][0], nvo[0][1], nvo[1][0], nvo[1][1]}; }
;     ...
;             X_LDB0(0, 0); X_LDB1(0, 1); G_SCHED; X_LDA(0, 0); G_STAGE_A(G_SA(1, 1), k1, vo[1][0], vo[1][1]);
;             G_WAIT_V(8); G_WAIT_L(0); G_BAR; X_MMA0(0, 0); X_MMA1(0, 1); G_BAR; G_SCHED;
;             X_LDA(0, 1); G_STAGE_B(G_SB(0, 0), b2); G_STAGE_B(G_SB(0, 1), b2 + hstep); G_STAGE_A(G_SA(0, 0), k2, w00, w01);
;             G_WAIT_V(8); G_WAIT_L(0); G_BAR; X_MMA0(1, 0); X_MMA1(1, 1); G_BAR; G_SCHED;
.Lmy_peel_gu_1006:
	v_lshl_add_u64 v[2:3], v[178:179], 0, s[42:43]
	v_cndmask_b32_e32 v188, v2, v176, vcc
	v_add_u32_e32 v2, 0x10000, v209
	v_add_u32_e32 v14, 0x14000, v209
	v_cndmask_b32_e32 v189, v3, v177, vcc
	ds_read_b128 v[18:21], v2
	ds_read_b128 v[22:25], v2 offset:1024
	ds_read_b128 v[26:29], v2 offset:2048
	ds_read_b128 v[30:33], v2 offset:3072
	ds_read_b128 v[2:5], v14
	ds_read_b128 v[6:9], v14 offset:1024
	ds_read_b128 v[10:13], v14 offset:2048
	ds_read_b128 v[14:17], v14 offset:3072
	s_add_u32 s12, s42, 0x100
	s_addc_u32 s13, s43, 0
	s_and_b64 s[24:25], vcc, exec
	s_cselect_b32 s24, 0, s12
	v_lshl_add_u64 v[192:193], v[182:183], 0, s[42:43]
	s_add_i32 m0, s3, 0xc000
	ds_read_b128 v[232:235], v210
	ds_read_b128 v[236:239], v210 offset:1024
	ds_read_b128 v[240:243], v210 offset:2048
	ds_read_b128 v[244:247], v210 offset:3072
	ds_read_b128 v[196:199], v210 offset:4096
	ds_read_b128 v[200:203], v210 offset:5120
	ds_read_b128 v[212:215], v210 offset:6144
	ds_read_b128 v[216:219], v210 offset:7168
	global_load_lds_dwordx4 v[192:193], off
	v_lshl_add_u64 v[192:193], v[180:181], 0, s[42:43]
	s_add_i32 m0, s3, 0xe000
	s_nop 0
	global_load_lds_dwordx4 v[192:193], off
	s_waitcnt vmcnt(8)
	s_waitcnt lgkmcnt(0)
	s_barrier
	s_setprio 1
	s_waitcnt lgkmcnt(0)
	v_mfma_scale_f32_16x16x128_f8f6f4 v[164:167], v[18:25], v[232:239], 0, v222, v222 op_sel_hi:[0,0,0]
	v_mfma_scale_f32_16x16x128_f8f6f4 v[160:163], v[26:33], v[232:239], 0, v222, v222 op_sel_hi:[0,0,0]
	v_mfma_scale_f32_16x16x128_f8f6f4 v[156:159], v[18:25], v[240:247], 0, v222, v222 op_sel_hi:[0,0,0]
	v_mfma_scale_f32_16x16x128_f8f6f4 v[152:155], v[26:33], v[240:247], 0, v222, v222 op_sel_hi:[0,0,0]
	v_mfma_scale_f32_16x16x128_f8f6f4 v[148:151], v[18:25], v[196:203], 0, v222, v222 op_sel_hi:[0,0,0]
	v_mfma_scale_f32_16x16x128_f8f6f4 v[144:147], v[26:33], v[196:203], 0, v222, v222 op_sel_hi:[0,0,0]
	v_mfma_scale_f32_16x16x128_f8f6f4 v[140:143], v[18:25], v[212:219], 0, v222, v222 op_sel_hi:[0,0,0]
	v_mfma_scale_f32_16x16x128_f8f6f4 v[136:139], v[26:33], v[212:219], 0, v222, v222 op_sel_hi:[0,0,0]
	s_setprio 0
	s_setprio 1
	v_mfma_scale_f32_16x16x128_f8f6f4 v[132:135], v[2:9], v[232:239], 0, v222, v222 op_sel_hi:[0,0,0]
	v_mfma_scale_f32_16x16x128_f8f6f4 v[128:131], v[10:17], v[232:239], 0, v222, v222 op_sel_hi:[0,0,0]
	v_mfma_scale_f32_16x16x128_f8f6f4 v[124:127], v[2:9], v[240:247], 0, v222, v222 op_sel_hi:[0,0,0]
	v_mfma_scale_f32_16x16x128_f8f6f4 v[120:123], v[10:17], v[240:247], 0, v222, v222 op_sel_hi:[0,0,0]
	v_mfma_scale_f32_16x16x128_f8f6f4 v[116:119], v[2:9], v[196:203], 0, v222, v222 op_sel_hi:[0,0,0]
	v_mfma_scale_f32_16x16x128_f8f6f4 v[112:115], v[10:17], v[196:203], 0, v222, v222 op_sel_hi:[0,0,0]
	v_mfma_scale_f32_16x16x128_f8f6f4 v[108:111], v[2:9], v[212:219], 0, v222, v222 op_sel_hi:[0,0,0]
	v_mfma_scale_f32_16x16x128_f8f6f4 v[104:107], v[10:17], v[212:219], 0, v222, v222 op_sel_hi:[0,0,0]
	s_setprio 0
	s_barrier
	s_mov_b32 m0, s27
	v_lshl_add_u64 v[188:189], v[188:189], 0, v[170:171]
	ds_read_b128 v[196:199], v210 offset:16384
	ds_read_b128 v[200:203], v210 offset:17408
	ds_read_b128 v[212:215], v210 offset:18432
	ds_read_b128 v[216:219], v210 offset:19456
	ds_read_b128 v[232:235], v210 offset:20480
	ds_read_b128 v[236:239], v210 offset:21504
	ds_read_b128 v[240:243], v210 offset:22528
	ds_read_b128 v[244:247], v210 offset:23552
	global_load_lds_dwordx4 v[188:189], off
	v_lshl_add_u64 v[192:193], v[188:189], 0, s[20:21]
	s_mov_b32 m0, s28
	s_add_u32 s42, s78, s24
	global_load_lds_dwordx4 v[192:193], off
	v_lshl_add_u64 v[192:193], v[188:189], 0, s[18:19]
	s_mov_b32 m0, s29
	s_addc_u32 s43, s79, 0
	global_load_lds_dwordx4 v[192:193], off
	v_lshl_add_u64 v[192:193], v[188:189], 0, s[92:93]
	s_mov_b32 m0, s51
	v_mov_b32_e32 v191, v67
	global_load_lds_dwordx4 v[192:193], off
	s_mov_b32 m0, s3
	v_lshl_add_u64 v[192:193], s[42:43], 0, v[66:67]
	global_load_lds_dwordx4 v66, s[42:43]
	s_mov_b32 m0, s68
	s_nop 0
	global_load_lds_dwordx4 v190, s[42:43]
	s_waitcnt vmcnt(8)
	s_cmp_eq_u32 s100, 1
	s_cbranch_scc0 .Lmy_gu_nvo_done
	v_lshrrev_b32_e32 v38, 1, v38
	v_lshrrev_b32_e32 v39, 1, v39
	v_lshrrev_b32_e32 v40, 1, v40
	v_lshrrev_b32_e32 v41, 1, v41
	v_lshl_add_u32 v38, v38, 10, v205
	v_lshl_add_u32 v39, v39, 10, v205
	v_lshl_add_u32 v40, v40, 10, v205
	v_lshl_add_u32 v41, v41, 10, v205
	ds_write_b128 v206, v[38:41]
; #define G_STAGE_B(bufoff, gbase) do { G_GLDS((const char*)(gbase) + voffB0, (bufoff) + ldsw); G_GLDS((const char*)(gbase) + vstep64 + voffB0, (bufoff) + ldsw + 8192); } while (0)
; #define G_STAGE_A(bufoff, kofs, v0, v1) do { G_GLDS((const char*)A + (kofs) + (v0), (bufoff) + ldsw); G_GLDS((const char*)A + (kofs) + (v1), (bufoff) + ldsw + 8192); } while (0)
; #define X_LDA(b, h) do { if constexpr (MODE == 2) G_LDA8(A8, b, h); else G_LDA(At, b, h); } while (0)
; #define X_LDB0(b, h) do { if constexpr (MODE == 2) G_LDB8(B08, b, h); else G_LDB(B0, b, h); } while (0)
; #define X_LDB1(b, h) do { if constexpr (MODE == 2) G_LDB8(B18, b, h); else G_LDB(B1, b, h); } while (0)
; #define X_MMA0(ai, bj) do { if constexpr (MODE == 2) G_MMA8(ai, bj, A8, B08); else G_MMA(ai, bj, At, B0); } while (0)
; #define X_MMA1(ai, bj) do { if constexpr (MODE == 2) G_MMA8(ai, bj, A8, B18); else G_MMA(ai, bj, At, B1); } while (0)
; #define G_WAIT_V(n) asm volatile("s_waitcnt vmcnt(" #n ")" ::: "memory")
; #define G_WAIT_L(n) asm volatile("s_waitcnt lgkmcnt(" #n ")" ::: "memory")
; #define G_BAR __builtin_amdgcn_s_barrier()
; #define G_SCHED __builtin_amdgcn_sched_barrier(0)
;     ...
;             G_WAIT_V(8); G_WAIT_L(0); G_BAR; X_MMA0(1, 0); X_MMA1(1, 1); G_BAR; G_SCHED;
;             X_LDB0(1, 0); X_LDB1(1, 1); G_SCHED; X_LDA(1, 0); G_STAGE_A(G_SA(0, 1), k2, w10, w11);
;             G_WAIT_V(8); G_WAIT_L(0); G_BAR; X_MMA0(0, 0); X_MMA1(0, 1); G_BAR; G_SCHED;
;             X_LDA(1, 1); G_STAGE_B(G_SB(1, 0), b3); G_STAGE_B(G_SB(1, 1), b3 + hstep); G_STAGE_A(G_SA(1, 0), k2 + kstep, w00, w01);
.Lmy_gu_nvo_done:
	s_waitcnt lgkmcnt(0)
	v_lshl_add_u64 v[190:191], s[42:43], 0, v[190:191]
	s_barrier
	s_setprio 1
	s_waitcnt lgkmcnt(0)
	v_mfma_scale_f32_16x16x128_f8f6f4 v[100:103], v[18:25], v[196:203], 0, v222, v222 op_sel_hi:[0,0,0]
	v_mfma_scale_f32_16x16x128_f8f6f4 v[96:99], v[26:33], v[196:203], 0, v222, v222 op_sel_hi:[0,0,0]
	v_mfma_scale_f32_16x16x128_f8f6f4 v[92:95], v[18:25], v[212:219], 0, v222, v222 op_sel_hi:[0,0,0]
	v_mfma_scale_f32_16x16x128_f8f6f4 v[88:91], v[26:33], v[212:219], 0, v222, v222 op_sel_hi:[0,0,0]
	v_mfma_scale_f32_16x16x128_f8f6f4 v[84:87], v[18:25], v[232:239], 0, v222, v222 op_sel_hi:[0,0,0]
	v_mfma_scale_f32_16x16x128_f8f6f4 v[80:83], v[26:33], v[232:239], 0, v222, v222 op_sel_hi:[0,0,0]
	v_mfma_scale_f32_16x16x128_f8f6f4 v[76:79], v[18:25], v[240:247], 0, v222, v222 op_sel_hi:[0,0,0]
	v_mfma_scale_f32_16x16x128_f8f6f4 v[72:75], v[26:33], v[240:247], 0, v222, v222 op_sel_hi:[0,0,0]
	s_setprio 0
	s_setprio 1
	v_mfma_scale_f32_16x16x128_f8f6f4 v[68:71], v[2:9], v[196:203], 0, v222, v222 op_sel_hi:[0,0,0]
	v_mfma_scale_f32_16x16x128_f8f6f4 v[62:65], v[10:17], v[196:203], 0, v222, v222 op_sel_hi:[0,0,0]
	v_mfma_scale_f32_16x16x128_f8f6f4 v[58:61], v[2:9], v[212:219], 0, v222, v222 op_sel_hi:[0,0,0]
	v_mfma_scale_f32_16x16x128_f8f6f4 v[54:57], v[10:17], v[212:219], 0, v222, v222 op_sel_hi:[0,0,0]
	v_mfma_scale_f32_16x16x128_f8f6f4 v[50:53], v[2:9], v[232:239], 0, v222, v222 op_sel_hi:[0,0,0]
	v_mfma_scale_f32_16x16x128_f8f6f4 v[46:49], v[10:17], v[232:239], 0, v222, v222 op_sel_hi:[0,0,0]
	v_mfma_scale_f32_16x16x128_f8f6f4 v[42:45], v[2:9], v[240:247], 0, v222, v222 op_sel_hi:[0,0,0]
	v_mfma_scale_f32_16x16x128_f8f6f4 v[38:41], v[10:17], v[240:247], 0, v222, v222 op_sel_hi:[0,0,0]
	s_setprio 0
	s_barrier
	v_add_u32_e32 v14, 0x18000, v209
	v_add_u32_e32 v30, 0x1c000, v209
	ds_read_b128 v[2:5], v14
	ds_read_b128 v[6:9], v14 offset:1024
	ds_read_b128 v[10:13], v14 offset:2048
	ds_read_b128 v[14:17], v14 offset:3072
	ds_read_b128 v[18:21], v30
	ds_read_b128 v[22:25], v30 offset:1024
	ds_read_b128 v[26:29], v30 offset:2048
	ds_read_b128 v[30:33], v30 offset:3072
	s_mov_b32 m0, s69
	v_lshl_add_u64 v[186:187], s[42:43], 0, v[186:187]
	ds_read_b128 v[196:199], v210 offset:32768
	ds_read_b128 v[200:203], v210 offset:33792
	ds_read_b128 v[212:215], v210 offset:34816
	ds_read_b128 v[216:219], v210 offset:35840
	ds_read_b128 v[232:235], v210 offset:36864
	ds_read_b128 v[236:239], v210 offset:37888
	ds_read_b128 v[240:243], v210 offset:38912
	ds_read_b128 v[244:247], v210 offset:39936
	global_load_lds_dwordx4 v[186:187], off
	v_lshl_add_u64 v[184:185], s[42:43], 0, v[184:185]
	s_mov_b32 m0, s72
	s_nop 0
	global_load_lds_dwordx4 v[184:185], off
	s_waitcnt vmcnt(8)
	s_waitcnt lgkmcnt(0)
	s_barrier
	s_setprio 1
	s_waitcnt lgkmcnt(0)
	v_mfma_scale_f32_16x16x128_f8f6f4 v[164:167], v[2:9], v[196:203], v[164:167], v222, v222 op_sel_hi:[0,0,0]
	v_mfma_scale_f32_16x16x128_f8f6f4 v[160:163], v[10:17], v[196:203], v[160:163], v222, v222 op_sel_hi:[0,0,0]
	v_mfma_scale_f32_16x16x128_f8f6f4 v[156:159], v[2:9], v[212:219], v[156:159], v222, v222 op_sel_hi:[0,0,0]
	v_mfma_scale_f32_16x16x128_f8f6f4 v[152:155], v[10:17], v[212:219], v[152:155], v222, v222 op_sel_hi:[0,0,0]
	v_mfma_scale_f32_16x16x128_f8f6f4 v[148:151], v[2:9], v[232:239], v[148:151], v222, v222 op_sel_hi:[0,0,0]
	v_mfma_scale_f32_16x16x128_f8f6f4 v[144:147], v[10:17], v[232:239], v[144:147], v222, v222 op_sel_hi:[0,0,0]
	v_mfma_scale_f32_16x16x128_f8f6f4 v[140:143], v[2:9], v[240:247], v[140:143], v222, v222 op_sel_hi:[0,0,0]
	v_mfma_scale_f32_16x16x128_f8f6f4 v[136:139], v[10:17], v[240:247], v[136:139], v222, v222 op_sel_hi:[0,0,0]
	s_setprio 0
	s_setprio 1
	v_mfma_scale_f32_16x16x128_f8f6f4 v[132:135], v[18:25], v[196:203], v[132:135], v222, v222 op_sel_hi:[0,0,0]
	v_mfma_scale_f32_16x16x128_f8f6f4 v[128:131], v[26:33], v[196:203], v[128:131], v222, v222 op_sel_hi:[0,0,0]
	v_mfma_scale_f32_16x16x128_f8f6f4 v[124:127], v[18:25], v[212:219], v[124:127], v222, v222 op_sel_hi:[0,0,0]
	v_mfma_scale_f32_16x16x128_f8f6f4 v[120:123], v[26:33], v[212:219], v[120:123], v222, v222 op_sel_hi:[0,0,0]
	v_mfma_scale_f32_16x16x128_f8f6f4 v[116:119], v[18:25], v[232:239], v[116:119], v222, v222 op_sel_hi:[0,0,0]
	v_mfma_scale_f32_16x16x128_f8f6f4 v[112:115], v[26:33], v[232:239], v[112:115], v222, v222 op_sel_hi:[0,0,0]
	v_mfma_scale_f32_16x16x128_f8f6f4 v[108:111], v[18:25], v[240:247], v[108:111], v222, v222 op_sel_hi:[0,0,0]
	v_mfma_scale_f32_16x16x128_f8f6f4 v[104:107], v[26:33], v[240:247], v[104:107], v222, v222 op_sel_hi:[0,0,0]
	s_setprio 0
	s_barrier
; #define G_STAGE_B(bufoff, gbase) do { G_GLDS((const char*)(gbase) + voffB0, (bufoff) + ldsw); G_GLDS((const char*)(gbase) + vstep64 + voffB0, (bufoff) + ldsw + 8192); } while (0)
; #define G_STAGE_A(bufoff, kofs, v0, v1) do { G_GLDS((const char*)A + (kofs) + (v0), (bufoff) + ldsw); G_GLDS((const char*)A + (kofs) + (v1), (bufoff) + ldsw + 8192); } while (0)
; #define X_LDA(b, h) do { if constexpr (MODE == 2) G_LDA8(A8, b, h); else G_LDA(At, b, h); } while (0)
; #define X_LDB0(b, h) do { if constexpr (MODE == 2) G_LDB8(B08, b, h); else G_LDB(B0, b, h); } while (0)
; #define X_LDB1(b, h) do { if constexpr (MODE == 2) G_LDB8(B18, b, h); else G_LDB(B1, b, h); } while (0)
; #define X_MMA0(ai, bj) do { if constexpr (MODE == 2) G_MMA8(ai, bj, A8, B08); else G_MMA(ai, bj, At, B0); } while (0)
; #define X_MMA1(ai, bj) do { if constexpr (MODE == 2) G_MMA8(ai, bj, A8, B18); else G_MMA(ai, bj, At, B1); } while (0)
; #define G_WAIT_V(n) asm volatile("s_waitcnt vmcnt(" #n ")" ::: "memory")
; #define G_WAIT_L(n) asm volatile("s_waitcnt lgkmcnt(" #n ")" ::: "memory")
; #define G_BAR __builtin_amdgcn_s_barrier()
; #define G_SCHED __builtin_amdgcn_sched_barrier(0)
;     ...
;             X_LDB0(1, 0); X_LDB1(1, 1); G_SCHED; X_LDA(1, 0); G_STAGE_A(G_SA(0, 1), k2, w10, w11);
;             G_WAIT_V(8); G_WAIT_L(0); G_BAR; X_MMA0(0, 0); X_MMA1(0, 1); G_BAR; G_SCHED;
;             X_LDA(1, 1); G_STAGE_B(G_SB(1, 0), b3); G_STAGE_B(G_SB(1, 1), b3 + hstep); G_STAGE_A(G_SA(1, 0), k2 + kstep, w00, w01);
;             G_WAIT_V(8); G_WAIT_L(0); G_BAR; X_MMA0(1, 0); X_MMA1(1, 1); G_BAR; G_SCHED;
;         }
	s_mov_b32 m0, s2
	v_lshl_add_u64 v[184:185], v[188:189], 0, s[82:83]
	ds_read_b128 v[196:199], v210 offset:49152
	ds_read_b128 v[200:203], v210 offset:50176
	ds_read_b128 v[212:215], v210 offset:51200
	ds_read_b128 v[216:219], v210 offset:52224
	ds_read_b128 v[232:235], v210 offset:53248
	ds_read_b128 v[236:239], v210 offset:54272
	ds_read_b128 v[240:243], v210 offset:55296
	ds_read_b128 v[244:247], v210 offset:56320
	global_load_lds_dwordx4 v[184:185], off
	v_lshl_add_u64 v[184:185], v[188:189], 0, s[22:23]
	s_mov_b32 m0, s73
	s_nop 0
	global_load_lds_dwordx4 v[184:185], off
	v_lshl_add_u64 v[184:185], v[188:189], 0, s[88:89]
	s_mov_b32 m0, s91
	s_nop 0
	global_load_lds_dwordx4 v[184:185], off
	v_lshl_add_u64 v[184:185], v[188:189], 0, s[74:75]
	s_mov_b32 m0, s94
	s_nop 0
	global_load_lds_dwordx4 v[184:185], off
	v_lshl_add_u64 v[184:185], v[192:193], 0, s[82:83]
	s_mov_b32 m0, s86
	s_nop 0
	global_load_lds_dwordx4 v[184:185], off
	v_lshl_add_u64 v[184:185], v[190:191], 0, s[82:83]
	s_mov_b32 m0, s90
	s_nop 0
	global_load_lds_dwordx4 v[184:185], off
	s_waitcnt vmcnt(8)
	s_waitcnt lgkmcnt(0)
	s_barrier
	s_setprio 1
	s_waitcnt lgkmcnt(0)
	v_mfma_scale_f32_16x16x128_f8f6f4 v[100:103], v[2:9], v[196:203], v[100:103], v222, v222 op_sel_hi:[0,0,0]
	v_mfma_scale_f32_16x16x128_f8f6f4 v[96:99], v[10:17], v[196:203], v[96:99], v222, v222 op_sel_hi:[0,0,0]
	v_mfma_scale_f32_16x16x128_f8f6f4 v[92:95], v[2:9], v[212:219], v[92:95], v222, v222 op_sel_hi:[0,0,0]
	v_mfma_scale_f32_16x16x128_f8f6f4 v[88:91], v[10:17], v[212:219], v[88:91], v222, v222 op_sel_hi:[0,0,0]
	v_mfma_scale_f32_16x16x128_f8f6f4 v[84:87], v[2:9], v[232:239], v[84:87], v222, v222 op_sel_hi:[0,0,0]
	v_mfma_scale_f32_16x16x128_f8f6f4 v[80:83], v[10:17], v[232:239], v[80:83], v222, v222 op_sel_hi:[0,0,0]
	v_mfma_scale_f32_16x16x128_f8f6f4 v[76:79], v[2:9], v[240:247], v[76:79], v222, v222 op_sel_hi:[0,0,0]
	v_mfma_scale_f32_16x16x128_f8f6f4 v[72:75], v[10:17], v[240:247], v[72:75], v222, v222 op_sel_hi:[0,0,0]
	s_setprio 0
	s_setprio 1
	v_mfma_scale_f32_16x16x128_f8f6f4 v[68:71], v[18:25], v[196:203], v[68:71], v222, v222 op_sel_hi:[0,0,0]
	v_mfma_scale_f32_16x16x128_f8f6f4 v[62:65], v[26:33], v[196:203], v[62:65], v222, v222 op_sel_hi:[0,0,0]
	v_mfma_scale_f32_16x16x128_f8f6f4 v[58:61], v[18:25], v[212:219], v[58:61], v222, v222 op_sel_hi:[0,0,0]
	v_mfma_scale_f32_16x16x128_f8f6f4 v[54:57], v[26:33], v[212:219], v[54:57], v222, v222 op_sel_hi:[0,0,0]
	v_mfma_scale_f32_16x16x128_f8f6f4 v[50:53], v[18:25], v[232:239], v[50:53], v222, v222 op_sel_hi:[0,0,0]
	v_mfma_scale_f32_16x16x128_f8f6f4 v[46:49], v[26:33], v[232:239], v[46:49], v222, v222 op_sel_hi:[0,0,0]
	v_mfma_scale_f32_16x16x128_f8f6f4 v[42:45], v[18:25], v[240:247], v[42:45], v222, v222 op_sel_hi:[0,0,0]
	v_mfma_scale_f32_16x16x128_f8f6f4 v[38:41], v[26:33], v[240:247], v[38:41], v222, v222 op_sel_hi:[0,0,0]
	s_setprio 0
	s_barrier
	s_add_i32 s7, s7, 2
	s_cmp_gt_u32 s7, 5
	s_cbranch_scc1 .LBB0_1008
	s_mov_b64 s[42:43], s[12:13]

; __global__ void __launch_bounds__(NTHR, 2) fwd_kernel(Args args) {
	.amdhsa_kernel _Z10fwd_kernel4Args
		.amdhsa_group_segment_fixed_size 0
		.amdhsa_private_segment_fixed_size 0
		.amdhsa_kernarg_size 416
		.amdhsa_user_sgpr_count 2
		.amdhsa_user_sgpr_dispatch_ptr 0
		.amdhsa_user_sgpr_queue_ptr 0
		.amdhsa_user_sgpr_kernarg_segment_ptr 1
		.amdhsa_user_sgpr_dispatch_id 0
		.amdhsa_user_sgpr_kernarg_preload_length 0
		.amdhsa_user_sgpr_kernarg_preload_offset 0
		.amdhsa_user_sgpr_private_segment_size 0
		.amdhsa_uses_dynamic_stack 0
		.amdhsa_enable_private_segment 0
		.amdhsa_system_sgpr_workgroup_id_x 1
		.amdhsa_system_sgpr_workgroup_id_y 0
		.amdhsa_system_sgpr_workgroup_id_z 0
		.amdhsa_system_sgpr_workgroup_info 0
		.amdhsa_system_vgpr_workitem_id 0
		.amdhsa_next_free_vgpr 256
		.amdhsa_next_free_sgpr 102
		.amdhsa_accum_offset 256
		.amdhsa_reserve_vcc 1
		.amdhsa_float_round_mode_32 0
		.amdhsa_float_round_mode_16_64 0
		.amdhsa_float_denorm_mode_32 3
		.amdhsa_float_denorm_mode_16_64 3
		.amdhsa_dx10_clamp 1
		.amdhsa_ieee_mode 1
		.amdhsa_fp16_overflow 0
		.amdhsa_tg_split 0
		.amdhsa_exception_fp_ieee_invalid_op 0
		.amdhsa_exception_fp_denorm_src 0
		.amdhsa_exception_fp_ieee_div_zero 0
		.amdhsa_exception_fp_ieee_overflow 0
		.amdhsa_exception_fp_ieee_underflow 0
		.amdhsa_exception_fp_ieee_inexact 0
		.amdhsa_exception_int_div_zero 0
	.end_amdhsa_kernel

; __global__ void __launch_bounds__(NTHR, 2) fwd_kernel(Args args) {
amdhsa.kernels:
  - .agpr_count:     0
    .args:
      - .offset:         0
        .size:           160
        .value_kind:     by_value
      - .offset:         160
        .size:           4
        .value_kind:     hidden_block_count_x
      - .offset:         164
        .size:           4
        .value_kind:     hidden_block_count_y
      - .offset:         168
        .size:           4
        .value_kind:     hidden_block_count_z
      - .offset:         172
        .size:           2
        .value_kind:     hidden_group_size_x
      - .offset:         174
        .size:           2
        .value_kind:     hidden_group_size_y
      - .offset:         176
        .size:           2
        .value_kind:     hidden_group_size_z
      - .offset:         178
        .size:           2
        .value_kind:     hidden_remainder_x
      - .offset:         180
        .size:           2
        .value_kind:     hidden_remainder_y
      - .offset:         182
        .size:           2
        .value_kind:     hidden_remainder_z
      - .offset:         200
        .size:           8
        .value_kind:     hidden_global_offset_x
      - .offset:         208
        .size:           8
        .value_kind:     hidden_global_offset_y
      - .offset:         216
        .size:           8
        .value_kind:     hidden_global_offset_z
      - .offset:         224
        .size:           2
        .value_kind:     hidden_grid_dims
      - .offset:         280
        .size:           4
        .value_kind:     hidden_dynamic_lds_size
    .group_segment_fixed_size: 0
    .kernarg_segment_align: 8
    .kernarg_segment_size: 416
    .language:       OpenCL C
    .language_version:
      - 2
      - 0
    .max_flat_workgroup_size: 512
    .name:           _Z10fwd_kernel4Args
    .private_segment_fixed_size: 0
    .sgpr_count:     108
    .sgpr_spill_count: 176
    .symbol:         _Z10fwd_kernel4Args.kd
    .uniform_work_group_size: 1
    .uses_dynamic_stack: false
    .vgpr_count:     256
    .vgpr_spill_count: 0
    .wavefront_size: 64
